# blocked H + static s_setprio 1 for waves 4-7 during attention
# speedup vs baseline: 1.0031x; 1.0003x over previous
; template <bool NOMAX> __device__ __forceinline__ void attn_all_t(Frame& F, char* lds, bf16* Obuf) {
;     attn_body::bf16x8 qr[4] = {};
;     bool first = true;
;     for (int L = F.vcu; L < 1536; L += F.G) {
;         long rowbase, n_rowbase; int NT, h, qb, kvh, n_NT, n_h, n_qb, n_kvh;
;         attn_decode(L, rowbase, NT, h, qb, kvh);
;         const bool has_next = L + F.G < 1536;
;         attn_decode(has_next ? L + F.G : L, n_rowbase, n_NT, n_h, n_qb, n_kvh);
;         const attn_body::bf16* Kh = (const attn_body::bf16*)F.KV + rowbase * 256 + kvh * 64;
;         const attn_body::bf16* n_Kh = (const attn_body::bf16*)F.KV + n_rowbase * 256 + n_kvh * 64;
;         attn_body::attn_unit<8, NOMAX>(rowbase, NT, h, qb, (const attn_body::bf16*)F.MIX, Kh, Kh + 128, (attn_body::bf16*)Obuf, lds, first, has_next, n_rowbase, n_h, n_qb, n_Kh, qr);
;         first = false;
;     }
.LBB0_1096:
	s_cmp_ge_u32 s53, 4
	s_cbranch_scc0 .Lattn_prio_done
	s_setprio 1
